# v9 (ResNorm stage-1 base loads 2 row groups in flight) with each modified phase padded so later code keeps its 64-byte alignment
# speedup vs baseline: 1.0035x; 1.0035x over previous
.LBB0_375:
	s_or_b64 exec, exec, s[36:37]
	v_or_b32_e32 v180, 16, v178
	v_ashrrev_i32_e32 v181, 31, v180
	v_lshlrev_b64 v[132:133], 13, v[180:181]
	v_or_b32_e32 v182, 32, v178
	v_ashrrev_i32_e32 v183, 31, v182
	v_lshlrev_b64 v[134:135], 13, v[182:183]
	v_or_b32_e32 v184, 48, v178
	v_ashrrev_i32_e32 v185, 31, v184
	v_lshlrev_b64 v[200:201], 13, v[184:185]
	v_add_u32_e32 v186, 0x80, v178
	v_ashrrev_i32_e32 v187, 31, v186
	v_lshlrev_b64 v[202:203], 13, v[186:187]
	v_add_u32_e32 v188, 0x90, v178
	v_ashrrev_i32_e32 v189, 31, v188
	v_lshlrev_b64 v[204:205], 13, v[188:189]
	v_add_u32_e32 v190, 0xa0, v178
	v_ashrrev_i32_e32 v191, 31, v190
	v_lshlrev_b64 v[206:207], 13, v[190:191]
	v_add_u32_e32 v192, 0xb0, v178
	v_ashrrev_i32_e32 v193, 31, v192
	v_lshlrev_b64 v[208:209], 13, v[192:193]
	s_nop 0
	s_nop 0
	s_nop 0
	s_nop 0
	s_nop 0
	s_nop 0
	s_nop 0
	s_nop 0
	s_waitcnt lgkmcnt(0)
	s_barrier
	s_cmpk_lt_u32 s3, 0x100
	s_cselect_b64 s[36:37], -1, 0
	s_cmpk_gt_u32 s3, 0xff
	s_cbranch_scc1 .LBB0_380
	v_add_u32_e32 v136, 0, v210
	v_add_u32_e32 v136, 0x20000, v136
	s_waitcnt lgkmcnt(0)
	ds_read_b128 v[136:139], v136
	s_ashr_i32 s31, s30, 31
	s_lshl_b64 s[14:15], s[30:31], 10
	v_lshl_add_u64 v[140:141], v[160:161], 0, s[14:15]
	s_waitcnt lgkmcnt(0)
	v_mov_b32_e32 v142, v137
	v_mov_b32_e32 v143, v138
	v_mov_b32_e32 v137, v139
	v_pk_add_f32 v[136:137], v[142:143], v[136:137]
	s_nop 0
	v_pk_add_f32 v[136:137], v[136:137], v[136:137] op_sel:[0,1] op_sel_hi:[1,0]
	global_store_dword v[140:141], v136, off sc1
	s_waitcnt vmcnt(0)
	s_and_saveexec_b64 s[38:39], s[6:7]
	s_cbranch_execz .LBB0_379
	s_mov_b64 s[40:41], exec
	v_mbcnt_lo_u32_b32 v136, s40, 0
	v_mbcnt_hi_u32_b32 v136, s41, v136
	v_cmp_eq_u32_e32 vcc, 0, v136
	s_and_b64 s[14:15], exec, vcc
	s_mov_b64 exec, s[14:15]
	s_cbranch_execz .LBB0_379
	s_lshl_b32 s14, s30, 6
	s_ashr_i32 s15, s14, 31
	s_lshl_b64 s[14:15], s[14:15], 2
	s_add_u32 s14, s56, s14
	s_addc_u32 s15, s57, s15
	s_bcnt1_i32_b64 s16, s[40:41]
	v_mov_b32_e32 v136, s16
	global_atomic_add v151, v136, s[14:15]

.LBB0_718:
	s_or_b64 exec, exec, s[40:41]
	v_or_b32_e32 v180, 16, v178
	v_ashrrev_i32_e32 v181, 31, v180
	v_lshlrev_b64 v[192:193], 13, v[180:181]
	v_or_b32_e32 v182, 32, v178
	v_ashrrev_i32_e32 v183, 31, v182
	v_lshlrev_b64 v[196:197], 13, v[182:183]
	v_or_b32_e32 v184, 48, v178
	v_ashrrev_i32_e32 v185, 31, v184
	v_lshlrev_b64 v[200:201], 13, v[184:185]
	v_add_u32_e32 v188, 0x80, v178
	v_ashrrev_i32_e32 v189, 31, v188
	v_lshlrev_b64 v[202:203], 13, v[188:189]
	v_add_u32_e32 v190, 0x90, v178
	v_ashrrev_i32_e32 v191, 31, v190
	v_lshlrev_b64 v[204:205], 13, v[190:191]
	v_add_u32_e32 v194, 0xa0, v178
	v_ashrrev_i32_e32 v195, 31, v194
	v_lshlrev_b64 v[206:207], 13, v[194:195]
	v_add_u32_e32 v198, 0xb0, v178
	v_ashrrev_i32_e32 v199, 31, v198
	v_lshlrev_b64 v[208:209], 13, v[198:199]
	s_nop 0
	s_nop 0
	s_nop 0
	s_nop 0
	s_nop 0
	s_nop 0
	s_nop 0
	s_waitcnt lgkmcnt(0)
	s_barrier
	s_cmpk_lt_u32 s3, 0x100
	s_cselect_b64 s[40:41], -1, 0
	s_cmpk_gt_u32 s3, 0xff
	s_cbranch_scc1 .LBB0_723
	v_add_u32_e32 v130, 0, v210
	v_add_u32_e32 v130, 0x20000, v130
	s_waitcnt lgkmcnt(0)
	ds_read_b128 v[130:133], v130
	s_ashr_i32 s37, s36, 31
	s_lshl_b64 s[14:15], s[36:37], 10
	v_lshl_add_u64 v[134:135], v[160:161], 0, s[14:15]
	s_waitcnt lgkmcnt(0)
	v_mov_b32_e32 v136, v131
	v_mov_b32_e32 v137, v132
	v_mov_b32_e32 v131, v133
	v_pk_add_f32 v[130:131], v[136:137], v[130:131]
	s_nop 0
	v_pk_add_f32 v[130:131], v[130:131], v[130:131] op_sel:[0,1] op_sel_hi:[1,0]
	global_store_dword v[134:135], v130, off sc1
	s_waitcnt vmcnt(0)
	s_and_saveexec_b64 s[42:43], s[6:7]
	s_cbranch_execz .LBB0_722
	s_mov_b64 s[44:45], exec
	v_mbcnt_lo_u32_b32 v130, s44, 0
	v_mbcnt_hi_u32_b32 v130, s45, v130
	v_cmp_eq_u32_e32 vcc, 0, v130
	s_and_b64 s[14:15], exec, vcc
	s_mov_b64 exec, s[14:15]
	s_cbranch_execz .LBB0_722
	s_lshl_b32 s14, s36, 6
	s_ashr_i32 s15, s14, 31
	s_lshl_b64 s[14:15], s[14:15], 2
	s_add_u32 s14, s61, s14
	s_addc_u32 s15, s62, s15
	s_bcnt1_i32_b64 s16, s[44:45]
	v_mov_b32_e32 v130, s16
	global_atomic_add v151, v130, s[14:15]

.LBB0_896:
	s_or_b64 exec, exec, s[38:39]
	v_or_b32_e32 v186, 16, v184
	v_ashrrev_i32_e32 v187, 31, v186
	v_lshlrev_b64 v[132:133], 13, v[186:187]
	v_or_b32_e32 v188, 32, v184
	v_ashrrev_i32_e32 v189, 31, v188
	v_lshlrev_b64 v[134:135], 13, v[188:189]
	v_or_b32_e32 v190, 48, v184
	v_ashrrev_i32_e32 v191, 31, v190
	v_lshlrev_b64 v[206:207], 13, v[190:191]
	v_add_u32_e32 v192, 0x80, v184
	v_ashrrev_i32_e32 v193, 31, v192
	v_lshlrev_b64 v[208:209], 13, v[192:193]
	v_add_u32_e32 v194, 0x90, v184
	v_ashrrev_i32_e32 v195, 31, v194
	v_lshlrev_b64 v[210:211], 13, v[194:195]
	v_add_u32_e32 v196, 0xa0, v184
	v_ashrrev_i32_e32 v197, 31, v196
	v_lshlrev_b64 v[212:213], 13, v[196:197]
	v_add_u32_e32 v198, 0xb0, v184
	v_ashrrev_i32_e32 v199, 31, v198
	v_lshlrev_b64 v[214:215], 13, v[198:199]
	s_nop 0
	s_nop 0
	s_nop 0
	s_nop 0
	s_nop 0
	s_nop 0
	s_nop 0
	s_nop 0
	s_waitcnt lgkmcnt(0)
	s_barrier
	s_cmpk_lt_u32 s3, 0x100
	s_cselect_b64 s[38:39], -1, 0
	s_cmpk_gt_u32 s3, 0xff
	s_cbranch_scc1 .LBB0_901
	v_add_u32_e32 v136, 0, v216
	v_add_u32_e32 v136, 0x20000, v136
	s_waitcnt lgkmcnt(0)
	ds_read_b128 v[136:139], v136
	s_ashr_i32 s35, s34, 31
	s_lshl_b64 s[14:15], s[34:35], 10
	v_lshl_add_u64 v[140:141], v[160:161], 0, s[14:15]
	s_waitcnt lgkmcnt(0)
	v_mov_b32_e32 v142, v137
	v_mov_b32_e32 v143, v138
	v_mov_b32_e32 v137, v139
	v_pk_add_f32 v[136:137], v[142:143], v[136:137]
	s_nop 0
	v_pk_add_f32 v[136:137], v[136:137], v[136:137] op_sel:[0,1] op_sel_hi:[1,0]
	global_store_dword v[140:141], v136, off sc1
	s_waitcnt vmcnt(0)
	s_and_saveexec_b64 s[40:41], s[6:7]
	s_cbranch_execz .LBB0_900
	s_mov_b64 s[42:43], exec
	v_mbcnt_lo_u32_b32 v136, s42, 0
	v_mbcnt_hi_u32_b32 v136, s43, v136
	v_cmp_eq_u32_e32 vcc, 0, v136
	s_and_b64 s[14:15], exec, vcc
	s_mov_b64 exec, s[14:15]
	s_cbranch_execz .LBB0_900
	s_lshl_b32 s14, s34, 6
	s_ashr_i32 s15, s14, 31
	s_lshl_b64 s[14:15], s[14:15], 2
	s_add_u32 s14, s66, s14
	s_addc_u32 s15, s67, s15
	s_bcnt1_i32_b64 s16, s[42:43]
	v_mov_b32_e32 v136, s16
	global_atomic_add v151, v136, s[14:15]

.LBB0_1516:
	s_or_b64 exec, exec, s[40:41]
	v_or_b32_e32 v180, 16, v178
	v_ashrrev_i32_e32 v181, 31, v180
	v_lshlrev_b64 v[192:193], 13, v[180:181]
	v_or_b32_e32 v182, 32, v178
	v_ashrrev_i32_e32 v183, 31, v182
	v_lshlrev_b64 v[196:197], 13, v[182:183]
	v_or_b32_e32 v184, 48, v178
	v_ashrrev_i32_e32 v185, 31, v184
	v_lshlrev_b64 v[200:201], 13, v[184:185]
	v_add_u32_e32 v188, 0x80, v178
	v_ashrrev_i32_e32 v189, 31, v188
	v_lshlrev_b64 v[202:203], 13, v[188:189]
	v_add_u32_e32 v190, 0x90, v178
	v_ashrrev_i32_e32 v191, 31, v190
	v_lshlrev_b64 v[204:205], 13, v[190:191]
	v_add_u32_e32 v194, 0xa0, v178
	v_ashrrev_i32_e32 v195, 31, v194
	v_lshlrev_b64 v[206:207], 13, v[194:195]
	v_add_u32_e32 v198, 0xb0, v178
	v_ashrrev_i32_e32 v199, 31, v198
	v_lshlrev_b64 v[208:209], 13, v[198:199]
	s_nop 0
	s_nop 0
	s_nop 0
	s_nop 0
	s_nop 0
	s_nop 0
	s_nop 0
	s_waitcnt lgkmcnt(0)
	s_barrier
	s_cmpk_lt_u32 s3, 0x100
	s_cselect_b64 s[40:41], -1, 0
	s_cmpk_gt_u32 s3, 0xff
	s_cbranch_scc1 .LBB0_1521
	v_add_u32_e32 v130, 0, v210
	v_add_u32_e32 v130, 0x20000, v130
	s_waitcnt lgkmcnt(0)
	ds_read_b128 v[130:133], v130
	s_ashr_i32 s37, s36, 31
	s_lshl_b64 s[14:15], s[36:37], 10
	v_lshl_add_u64 v[134:135], v[160:161], 0, s[14:15]
	s_waitcnt lgkmcnt(0)
	v_mov_b32_e32 v136, v131
	v_mov_b32_e32 v137, v132
	v_mov_b32_e32 v131, v133
	v_pk_add_f32 v[130:131], v[136:137], v[130:131]
	s_nop 0
	v_pk_add_f32 v[130:131], v[130:131], v[130:131] op_sel:[0,1] op_sel_hi:[1,0]
	global_store_dword v[134:135], v130, off sc1
	s_waitcnt vmcnt(0)
	s_and_saveexec_b64 s[42:43], s[6:7]
	s_cbranch_execz .LBB0_1520
	s_mov_b64 s[44:45], exec
	v_mbcnt_lo_u32_b32 v130, s44, 0
	v_mbcnt_hi_u32_b32 v130, s45, v130
	v_cmp_eq_u32_e32 vcc, 0, v130
	s_and_b64 s[14:15], exec, vcc
	s_mov_b64 exec, s[14:15]
	s_cbranch_execz .LBB0_1520
	s_lshl_b32 s14, s36, 6
	s_ashr_i32 s15, s14, 31
	s_lshl_b64 s[14:15], s[14:15], 2
	s_add_u32 s14, s59, s14
	s_addc_u32 s15, s60, s15
	s_bcnt1_i32_b64 s0, s[44:45]
	v_mov_b32_e32 v130, s0
	global_atomic_add v151, v130, s[14:15]
